# GEMM prologues (all six phases): both K-tiles' LDS-DMA loads requested before the first wait (vmcnt(8) instead of vmcnt(2) between them), removing one memory latency per phase start
# speedup vs baseline: 1.0145x; 1.0029x over previous
.LBB0_183:
	s_lshl_b32 s11, s17, 5
	s_and_b32 s21, s11, 0x60
	s_add_i32 m0, s28, 0x18000
	v_lshl_add_u64 v[6:7], v[6:7], 0, s[38:39]
	s_lshl_b32 s20, s9, 13
	s_lshl_b32 s17, s21, 7
	s_nop 0
	global_load_lds_dwordx4 v[6:7], off
	v_lshl_add_u64 v[4:5], v[4:5], 0, s[38:39]
	s_add_i32 m0, s28, 0x1a000
	s_add_i32 s84, s28, 0x8000
	s_add_i32 s85, s28, 0xa000
	global_load_lds_dwordx4 v[4:5], off
	v_lshl_add_u64 v[0:1], v[0:1], 0, s[38:39]
	s_mov_b32 m0, s84
	s_add_u32 s18, s72, 0x40080
	global_load_lds_dwordx4 v[0:1], off
	v_lshl_add_u64 v[0:1], v[2:3], 0, s[38:39]
	s_mov_b32 m0, s85
	s_addc_u32 s19, s73, 0
	global_load_lds_dwordx4 v[0:1], off
	s_add_i32 m0, s28, 0x1c000
	v_lshl_add_u64 v[0:1], s[18:19], 0, v[32:33]
	global_load_lds_dwordx4 v[0:1], off
	v_lshl_add_u64 v[0:1], s[18:19], 0, v[134:135]
	s_add_i32 m0, s28, 0x1e000
	s_cmpk_lt_u32 s8, 0x100
	global_load_lds_dwordx4 v[0:1], off
	s_waitcnt vmcnt(8)
	s_barrier
	v_lshrrev_b32_e32 v1, 1, v180
	v_and_b32_e32 v1, 24, v1
	v_and_b32_e32 v0, 15, v180
	v_lshlrev_b32_e32 v2, 1, v1
	v_lshl_or_b32 v150, s9, 6, v0
	v_lshl_or_b32 v0, v0, 6, v2
	v_lshlrev_b32_e32 v2, 2, v180
	v_and_b32_e32 v2, 32, v2
	v_bitop3_b32 v3, v0, s20, v2 bitop3:0xde
	v_bitop3_b32 v151, s17, v0, v2 bitop3:0xf6
	v_lshlrev_b32_e32 v0, 14, v8
	v_and_b32_e32 v0, 0xffff8000, v0
	v_or_b32_e32 v152, s21, v1
	v_lshl_add_u32 v0, v9, 11, v0
	v_and_b32_e32 v1, 1, v8
	v_lshl_or_b32 v0, v1, 6, v0
	v_lshl_add_u32 v136, v10, 1, v0
	v_lshlrev_b32_e32 v0, 14, v11
	v_and_b32_e32 v0, 0xffff8000, v0
	s_waitcnt vmcnt(6)
	v_lshl_add_u32 v0, v12, 11, v0
	v_and_b32_e32 v1, 1, v11
	v_lshl_or_b32 v0, v1, 6, v0
	s_sext_i32_i8 s11, s16
	s_cselect_b64 s[16:17], -1, 0
	v_mov_b32_e32 v137, v33
	v_lshl_add_u32 v138, v13, 1, v0
	v_mov_b32_e32 v139, v33
	s_mov_b32 s86, 0
	v_add_u32_e32 v153, 0, v3
	s_barrier
	s_branch .LBB0_186

.LBB0_205:
	v_lshl_add_u64 v[0:1], s[72:73], 0, v[32:33]
	v_mov_b32_e32 v167, v33
	v_lshl_add_u64 v[2:3], s[72:73], 0, v[166:167]
	v_mov_b32_e32 v163, v33
	v_lshlrev_b32_e32 v9, 2, v213
	s_lshl_b32 s9, s9, 5
	s_add_i32 m0, s83, 0x18000
	v_lshl_add_u64 v[0:1], v[0:1], 0, s[38:39]
	v_lshl_add_u64 v[4:5], s[10:11], 0, v[162:163]
	v_mov_b32_e32 v165, v33
	v_lshl_or_b32 v207, s14, 6, v213
	v_lshl_or_b32 v8, v213, 6, v214
	s_lshl_b32 s14, s14, 13
	v_and_b32_e32 v9, 32, v9
	s_and_b32 s9, s9, 0x60
	s_nop 0
	global_load_lds_dwordx4 v[0:1], off
	v_lshl_add_u64 v[0:1], v[2:3], 0, s[38:39]
	s_add_i32 m0, s83, 0x1a000
	s_add_i32 s85, s83, 0x8000
	s_add_i32 s86, s83, 0xa000
	v_lshl_add_u64 v[6:7], s[10:11], 0, v[164:165]
	v_bitop3_b32 v8, v8, s14, v9 bitop3:0xde
	global_load_lds_dwordx4 v[0:1], off
	v_lshl_add_u64 v[0:1], v[4:5], 0, s[38:39]
	s_mov_b32 m0, s85
	s_add_u32 s14, s72, 0x20080
	global_load_lds_dwordx4 v[0:1], off
	v_lshl_add_u64 v[0:1], v[6:7], 0, s[38:39]
	s_mov_b32 m0, s86
	s_addc_u32 s15, s73, 0
	global_load_lds_dwordx4 v[0:1], off
	s_add_i32 m0, s83, 0x1c000
	v_lshl_add_u64 v[0:1], s[14:15], 0, v[32:33]
	global_load_lds_dwordx4 v[0:1], off
	v_lshl_add_u64 v[0:1], s[14:15], 0, v[166:167]
	s_add_i32 m0, s83, 0x1e000
	s_cmpk_lt_u32 s8, 0x100
	global_load_lds_dwordx4 v[0:1], off
	s_waitcnt vmcnt(8)
	s_barrier
	v_lshlrev_b32_e32 v0, 13, v181
	v_and_b32_e32 v0, 0xffffc000, v0
	v_lshl_add_u32 v0, v182, 10, v0
	v_and_b32_e32 v1, 1, v181
	v_lshl_or_b32 v0, v1, 6, v0
	v_lshl_add_u32 v168, v183, 1, v0
	v_lshlrev_b32_e32 v0, 13, v184
	s_mov_b32 s8, s30
	v_lshl_or_b32 v208, s9, 7, v215
	v_or_b32_e32 v209, s9, v212
	v_and_b32_e32 v0, 0xffffc000, v0
	v_writelane_b32 v253, s8, 14
	s_waitcnt vmcnt(6)
	v_lshl_add_u32 v0, v185, 10, v0
	v_and_b32_e32 v1, 1, v184
	v_writelane_b32 v253, s9, 15
	v_lshl_or_b32 v0, v1, 6, v0
	v_readlane_b32 s8, v253, 16
	s_cselect_b64 s[20:21], -1, 0
	v_mov_b32_e32 v169, v33
	v_lshl_add_u32 v170, v211, 1, v0
	v_mov_b32_e32 v171, v33
	s_mov_b32 s87, 0
	v_add_u32_e32 v210, 0, v8
	s_mov_b32 s89, s30
	s_mov_b32 s88, s8
	s_barrier
	v_readlane_b32 s9, v253, 17
	s_branch .LBB0_208

.LBB0_485:
	v_readlane_b32 s16, v254, 30
	v_mov_b32_e32 v163, v33
	v_readlane_b32 s17, v254, 31
	v_mov_b32_e32 v165, v33
	s_lshl_b32 s2, s14, 5
	v_lshl_add_u64 v[90:91], s[16:17], 0, v[162:163]
	v_lshl_add_u64 v[92:93], s[16:17], 0, v[164:165]
	s_add_i32 s17, 0, 0x18000
	s_and_b32 s45, s2, 0x60
	s_add_i32 s2, s17, s9
	s_lshl_b32 s16, s44, 13
	v_lshl_add_u64 v[68:69], v[78:79], 0, s[38:39]
	s_mov_b32 m0, s2
	s_add_i32 s73, s2, 0x2000
	s_add_i32 s67, s77, 0x8000
	s_add_i32 s74, s77, 0xa000
	s_nop 0
	global_load_lds_dwordx4 v[68:69], off
	v_lshl_add_u64 v[70:71], v[80:81], 0, s[38:39]
	s_mov_b32 m0, s73
	s_add_u32 s14, s10, 0x20080
	global_load_lds_dwordx4 v[70:71], off
	v_lshl_add_u64 v[66:67], v[90:91], 0, s[38:39]
	s_mov_b32 m0, s67
	s_addc_u32 s15, s11, 0
	s_add_i32 s18, 0, 0x1c000
	global_load_lds_dwordx4 v[66:67], off
	v_lshl_add_u64 v[72:73], v[92:93], 0, s[38:39]
	s_mov_b32 m0, s74
	s_add_i32 s75, s18, s9
	global_load_lds_dwordx4 v[72:73], off
	v_lshl_add_u64 v[74:75], s[14:15], 0, v[32:33]
	s_mov_b32 m0, s75
	s_add_i32 s76, s75, 0x2000
	global_load_lds_dwordx4 v[74:75], off
	v_lshl_add_u64 v[76:77], s[14:15], 0, v[166:167]
	s_mov_b32 m0, s76
	v_lshlrev_b32_e32 v1, 2, v213
	global_load_lds_dwordx4 v[76:77], off
	s_waitcnt vmcnt(8)
	s_barrier
	v_lshl_or_b32 v0, v213, 6, v214
	v_and_b32_e32 v1, 32, v1
	v_bitop3_b32 v0, v0, s16, v1 bitop3:0xde
	v_lshl_or_b32 v1, s45, 7, v215
	s_add_i32 s85, 0, 0x10000
	v_add_u32_e32 v98, s85, v1
	s_add_i32 s85, s85, s9
	s_add_i32 s87, 0, 0x14000
	s_add_i32 s89, s77, 0xc000
	s_add_i32 s88, s77, 0xe000
	s_add_i32 s84, s85, 0x2000
	s_add_u32 s34, s10, 0x20100
	v_add_u32_e32 v97, s87, v1
	s_addc_u32 s35, s11, 0
	s_add_i32 s87, s87, s9
	s_waitcnt vmcnt(6)
	s_barrier
	s_add_i32 s86, s87, 0x2000
	ds_read_b128 v[4:7], v98
	ds_read_b128 v[8:11], v98 offset:1024
	ds_read_b128 v[16:19], v98 offset:2048
	ds_read_b128 v[20:23], v98 offset:3072
	ds_read_b128 v[100:103], v97
	ds_read_b128 v[104:107], v97 offset:1024
	ds_read_b128 v[108:111], v97 offset:2048
	ds_read_b128 v[112:115], v97 offset:3072
	s_add_u32 s20, s10, 0x20180
	s_addc_u32 s21, s11, 0
	v_add_u32_e32 v95, s18, v1
	s_add_u32 s18, s10, 0x20200
	s_addc_u32 s19, s11, 0
	v_readlane_b32 s14, v254, 16
	s_add_u32 s16, s10, 0x20280
	v_readlane_b32 s15, v254, 17
	v_add_u32_e32 v96, s17, v1
	s_addc_u32 s17, s11, 0
	v_lshl_add_u64 v[86:87], s[14:15], 0, v[162:163]
	v_lshl_add_u64 v[88:89], s[14:15], 0, v[164:165]
	s_add_u32 s14, s10, 0x20300
	s_addc_u32 s15, s11, 0
	s_add_u32 s10, s10, 0x20380
	s_addc_u32 s11, s11, 0
	v_add_u32_e32 v94, 0, v0
	s_cmpk_gt_u32 s8, 0xff
	v_readlane_b32 s8, v254, 18
	v_readlane_b32 s9, v254, 19
	s_mov_b32 m0, s89
	ds_read_b128 v[34:37], v94
	ds_read_b128 v[38:41], v94 offset:1024
	ds_read_b128 v[116:119], v94 offset:2048
	ds_read_b128 v[120:123], v94 offset:3072
	ds_read_b128 v[124:127], v94 offset:4096
	ds_read_b128 v[128:131], v94 offset:5120
	ds_read_b128 v[132:135], v94 offset:6144
	ds_read_b128 v[136:139], v94 offset:7168
	v_lshl_add_u64 v[0:1], s[8:9], 0, v[162:163]
	global_load_lds_dwordx4 v[0:1], off
	v_lshl_add_u64 v[0:1], s[8:9], 0, v[164:165]
	s_mov_b32 m0, s88
	s_nop 0
	global_load_lds_dwordx4 v[0:1], off
	s_waitcnt vmcnt(8)
	s_waitcnt lgkmcnt(0)
	s_barrier
	s_setprio 1
	s_mov_b32 s28, s29
	s_mov_b32 s30, s29
	s_mov_b32 s31, s29
	v_mov_b64_e32 v[64:65], s[30:31]
	v_mov_b64_e32 v[60:61], s[30:31]
	v_mov_b64_e32 v[48:49], s[30:31]
	v_mov_b64_e32 v[44:45], s[30:31]
	v_mov_b64_e32 v[28:29], s[28:29]
	v_mov_b64_e32 v[24:25], s[28:29]
	v_mov_b64_e32 v[12:13], s[28:29]
	v_mov_b64_e32 v[62:63], s[28:29]
	v_mov_b64_e32 v[58:59], s[28:29]
	v_mov_b64_e32 v[46:47], s[28:29]
	v_mov_b64_e32 v[42:43], s[28:29]
	v_mov_b64_e32 v[30:31], s[30:31]
	v_mov_b64_e32 v[26:27], s[30:31]
	v_mov_b64_e32 v[14:15], s[30:31]
	v_mov_b64_e32 v[0:1], s[28:29]
	s_waitcnt lgkmcnt(0)
	v_mfma_f32_16x16x128_f8f6f4 v[62:65], v[4:11], v[34:41], v[62:65]
	v_mfma_f32_16x16x128_f8f6f4 v[58:61], v[16:23], v[34:41], v[58:61]
	v_mfma_f32_16x16x128_f8f6f4 v[46:49], v[4:11], v[116:123], v[46:49]
	v_mfma_f32_16x16x128_f8f6f4 v[42:45], v[16:23], v[116:123], v[42:45]
	v_mfma_f32_16x16x128_f8f6f4 v[28:31], v[4:11], v[124:131], v[28:31]
	v_mfma_f32_16x16x128_f8f6f4 v[24:27], v[16:23], v[124:131], v[24:27]
	v_mfma_f32_16x16x128_f8f6f4 v[12:15], v[4:11], v[132:139], v[12:15]
	v_mov_b64_e32 v[8:9], s[28:29]
	v_mov_b64_e32 v[2:3], s[30:31]
	v_mov_b64_e32 v[10:11], s[30:31]
	v_mfma_f32_16x16x128_f8f6f4 v[8:11], v[16:23], v[132:139], v[8:11]
	s_setprio 0
	s_setprio 1
	v_mov_b64_e32 v[56:57], s[30:31]
	v_mov_b64_e32 v[52:53], s[30:31]
	v_mov_b64_e32 v[54:55], s[28:29]
	v_mov_b64_e32 v[50:51], s[28:29]
	v_mfma_f32_16x16x128_f8f6f4 v[54:57], v[100:107], v[34:41], v[54:57]
	v_mfma_f32_16x16x128_f8f6f4 v[50:53], v[108:115], v[34:41], v[50:53]
	v_mov_b64_e32 v[40:41], s[30:31]
	v_mov_b64_e32 v[36:37], s[30:31]
	v_mov_b64_e32 v[20:21], s[28:29]
	v_mov_b64_e32 v[16:17], s[28:29]
	v_mov_b64_e32 v[4:5], s[28:29]
	v_mov_b64_e32 v[38:39], s[28:29]
	v_mov_b64_e32 v[34:35], s[28:29]
	v_mov_b64_e32 v[22:23], s[30:31]
	v_mov_b64_e32 v[18:19], s[30:31]
	v_mov_b64_e32 v[6:7], s[30:31]
	v_mfma_f32_16x16x128_f8f6f4 v[38:41], v[100:107], v[116:123], v[38:41]
	v_mfma_f32_16x16x128_f8f6f4 v[34:37], v[108:115], v[116:123], v[34:37]
	v_mfma_f32_16x16x128_f8f6f4 v[20:23], v[100:107], v[124:131], v[20:23]
	v_mfma_f32_16x16x128_f8f6f4 v[16:19], v[108:115], v[124:131], v[16:19]
	v_mfma_f32_16x16x128_f8f6f4 v[4:7], v[100:107], v[132:139], v[4:7]
	v_mfma_f32_16x16x128_f8f6f4 v[0:3], v[108:115], v[132:139], v[0:3]
	s_setprio 0
	s_barrier
	s_mov_b64 s[8:9], 0x100
	s_mov_b32 m0, s85
	v_lshl_add_u64 v[100:101], v[78:79], 0, s[8:9]
	global_load_lds_dwordx4 v[100:101], off
	v_lshl_add_u64 v[100:101], v[80:81], 0, s[8:9]
	s_mov_b32 m0, s84
	s_nop 0
	global_load_lds_dwordx4 v[100:101], off
	v_lshl_add_u64 v[100:101], s[34:35], 0, v[32:33]
	s_mov_b32 m0, s87
	s_nop 0
	global_load_lds_dwordx4 v[100:101], off
	v_lshl_add_u64 v[100:101], s[34:35], 0, v[166:167]
	s_mov_b32 m0, s86
	s_nop 0
	global_load_lds_dwordx4 v[100:101], off
	v_lshl_add_u64 v[100:101], v[90:91], 0, s[8:9]
	s_mov_b32 m0, s77
	s_nop 0
	global_load_lds_dwordx4 v[100:101], off
	v_lshl_add_u64 v[100:101], v[92:93], 0, s[8:9]
	s_mov_b32 m0, s83
	s_nop 0
	global_load_lds_dwordx4 v[100:101], off
	s_waitcnt vmcnt(8)
	s_waitcnt lgkmcnt(0)
	s_barrier
	s_barrier
	ds_read_b128 v[100:103], v96
	ds_read_b128 v[104:107], v96 offset:1024
	ds_read_b128 v[108:111], v96 offset:2048
	ds_read_b128 v[112:115], v96 offset:3072
	ds_read_b128 v[116:119], v95
	ds_read_b128 v[120:123], v95 offset:1024
	ds_read_b128 v[124:127], v95 offset:2048
	ds_read_b128 v[128:131], v95 offset:3072
	v_readlane_b32 s8, v254, 20
	v_readlane_b32 s9, v254, 21
	s_mov_b32 m0, s66
	ds_read_b128 v[132:135], v94 offset:32768
	ds_read_b128 v[136:139], v94 offset:33792
	ds_read_b128 v[140:143], v94 offset:34816
	ds_read_b128 v[144:147], v94 offset:35840
	ds_read_b128 v[148:151], v94 offset:36864
	ds_read_b128 v[152:155], v94 offset:37888
	ds_read_b128 v[168:171], v94 offset:38912
	ds_read_b128 v[172:175], v94 offset:39936
	v_lshl_add_u64 v[156:157], s[8:9], 0, v[162:163]
	global_load_lds_dwordx4 v[156:157], off
	v_lshl_add_u64 v[156:157], s[8:9], 0, v[164:165]
	s_mov_b32 m0, s72
	s_nop 0
	global_load_lds_dwordx4 v[156:157], off
	s_waitcnt vmcnt(8)
	s_waitcnt lgkmcnt(0)
	s_barrier
	s_setprio 1
	s_waitcnt lgkmcnt(0)
	v_mfma_f32_16x16x128_f8f6f4 v[62:65], v[100:107], v[132:139], v[62:65]
	v_mfma_f32_16x16x128_f8f6f4 v[58:61], v[108:115], v[132:139], v[58:61]
	v_mfma_f32_16x16x128_f8f6f4 v[46:49], v[100:107], v[140:147], v[46:49]
	v_mfma_f32_16x16x128_f8f6f4 v[42:45], v[108:115], v[140:147], v[42:45]
	v_mfma_f32_16x16x128_f8f6f4 v[28:31], v[100:107], v[148:155], v[28:31]
	v_mfma_f32_16x16x128_f8f6f4 v[24:27], v[108:115], v[148:155], v[24:27]
	v_mfma_f32_16x16x128_f8f6f4 v[12:15], v[100:107], v[168:175], v[12:15]
	v_mfma_f32_16x16x128_f8f6f4 v[8:11], v[108:115], v[168:175], v[8:11]
	s_setprio 0
	s_setprio 1
	v_mfma_f32_16x16x128_f8f6f4 v[54:57], v[116:123], v[132:139], v[54:57]
	v_mfma_f32_16x16x128_f8f6f4 v[50:53], v[124:131], v[132:139], v[50:53]
	v_mfma_f32_16x16x128_f8f6f4 v[38:41], v[116:123], v[140:147], v[38:41]
	v_mfma_f32_16x16x128_f8f6f4 v[34:37], v[124:131], v[140:147], v[34:37]
	v_mfma_f32_16x16x128_f8f6f4 v[20:23], v[116:123], v[148:155], v[20:23]
	v_mfma_f32_16x16x128_f8f6f4 v[16:19], v[124:131], v[148:155], v[16:19]
	v_mfma_f32_16x16x128_f8f6f4 v[4:7], v[116:123], v[168:175], v[4:7]
	v_mfma_f32_16x16x128_f8f6f4 v[0:3], v[124:131], v[168:175], v[0:3]
	s_setprio 0
	s_barrier
	s_mov_b64 s[8:9], 0x180
	s_mov_b32 m0, s2
	v_lshl_add_u64 v[100:101], v[78:79], 0, s[8:9]
	global_load_lds_dwordx4 v[100:101], off
	v_lshl_add_u64 v[100:101], v[80:81], 0, s[8:9]
	s_mov_b32 m0, s73
	s_nop 0
	global_load_lds_dwordx4 v[100:101], off
	v_lshl_add_u64 v[100:101], s[20:21], 0, v[32:33]
	s_mov_b32 m0, s75
	s_nop 0
	global_load_lds_dwordx4 v[100:101], off
	v_lshl_add_u64 v[100:101], s[20:21], 0, v[166:167]
	s_mov_b32 m0, s76
	s_nop 0
	global_load_lds_dwordx4 v[100:101], off
	v_lshl_add_u64 v[100:101], v[90:91], 0, s[8:9]
	s_mov_b32 m0, s67
	s_nop 0
	global_load_lds_dwordx4 v[100:101], off
	v_lshl_add_u64 v[100:101], v[92:93], 0, s[8:9]
	s_mov_b32 m0, s74
	s_nop 0
	global_load_lds_dwordx4 v[100:101], off
	s_waitcnt vmcnt(8)
	s_waitcnt lgkmcnt(0)
	s_barrier
	s_barrier
	ds_read_b128 v[100:103], v98
	ds_read_b128 v[104:107], v98 offset:1024
	ds_read_b128 v[108:111], v98 offset:2048
	ds_read_b128 v[112:115], v98 offset:3072
	ds_read_b128 v[116:119], v97
	ds_read_b128 v[120:123], v97 offset:1024
	ds_read_b128 v[124:127], v97 offset:2048
	ds_read_b128 v[128:131], v97 offset:3072
	v_readlane_b32 s8, v254, 22
	v_readlane_b32 s9, v254, 23
	s_mov_b32 m0, s89
	ds_read_b128 v[132:135], v94
	ds_read_b128 v[136:139], v94 offset:1024
	ds_read_b128 v[140:143], v94 offset:2048
	ds_read_b128 v[144:147], v94 offset:3072
	ds_read_b128 v[148:151], v94 offset:4096
	ds_read_b128 v[152:155], v94 offset:5120
	ds_read_b128 v[168:171], v94 offset:6144
	ds_read_b128 v[172:175], v94 offset:7168
	v_lshl_add_u64 v[156:157], s[8:9], 0, v[162:163]
	global_load_lds_dwordx4 v[156:157], off
	v_lshl_add_u64 v[156:157], s[8:9], 0, v[164:165]
	s_mov_b32 m0, s88
	s_nop 0
	global_load_lds_dwordx4 v[156:157], off
	s_waitcnt vmcnt(8)
	s_waitcnt lgkmcnt(0)
	s_barrier
	s_setprio 1
	s_waitcnt lgkmcnt(0)
	v_mfma_f32_16x16x128_f8f6f4 v[62:65], v[100:107], v[132:139], v[62:65]
	v_mfma_f32_16x16x128_f8f6f4 v[58:61], v[108:115], v[132:139], v[58:61]
	v_mfma_f32_16x16x128_f8f6f4 v[46:49], v[100:107], v[140:147], v[46:49]
	v_mfma_f32_16x16x128_f8f6f4 v[42:45], v[108:115], v[140:147], v[42:45]
	v_mfma_f32_16x16x128_f8f6f4 v[28:31], v[100:107], v[148:155], v[28:31]
	v_mfma_f32_16x16x128_f8f6f4 v[24:27], v[108:115], v[148:155], v[24:27]
	v_mfma_f32_16x16x128_f8f6f4 v[12:15], v[100:107], v[168:175], v[12:15]
	v_mfma_f32_16x16x128_f8f6f4 v[8:11], v[108:115], v[168:175], v[8:11]
	s_setprio 0
	s_setprio 1
	v_mfma_f32_16x16x128_f8f6f4 v[54:57], v[116:123], v[132:139], v[54:57]
	v_mfma_f32_16x16x128_f8f6f4 v[50:53], v[124:131], v[132:139], v[50:53]
	v_mfma_f32_16x16x128_f8f6f4 v[38:41], v[116:123], v[140:147], v[38:41]
	v_mfma_f32_16x16x128_f8f6f4 v[34:37], v[124:131], v[140:147], v[34:37]
	v_mfma_f32_16x16x128_f8f6f4 v[20:23], v[116:123], v[148:155], v[20:23]
	v_mfma_f32_16x16x128_f8f6f4 v[16:19], v[124:131], v[148:155], v[16:19]
	v_mfma_f32_16x16x128_f8f6f4 v[4:7], v[116:123], v[168:175], v[4:7]
	v_mfma_f32_16x16x128_f8f6f4 v[0:3], v[124:131], v[168:175], v[0:3]
	s_setprio 0
	s_barrier
	s_mov_b64 s[8:9], 0x200
	s_mov_b32 m0, s85
	v_lshl_add_u64 v[100:101], v[78:79], 0, s[8:9]
	global_load_lds_dwordx4 v[100:101], off
	v_lshl_add_u64 v[100:101], v[80:81], 0, s[8:9]
	s_mov_b32 m0, s84
	s_nop 0
	global_load_lds_dwordx4 v[100:101], off
	v_lshl_add_u64 v[100:101], s[18:19], 0, v[32:33]
	s_mov_b32 m0, s87
	s_nop 0
	global_load_lds_dwordx4 v[100:101], off
	v_lshl_add_u64 v[100:101], s[18:19], 0, v[166:167]
	s_mov_b32 m0, s86
	s_nop 0
	global_load_lds_dwordx4 v[100:101], off
	v_lshl_add_u64 v[100:101], v[90:91], 0, s[8:9]
	s_mov_b32 m0, s77
	s_nop 0
	global_load_lds_dwordx4 v[100:101], off
	v_lshl_add_u64 v[100:101], v[92:93], 0, s[8:9]
	s_mov_b32 m0, s83
	s_nop 0
	global_load_lds_dwordx4 v[100:101], off
	s_waitcnt vmcnt(8)
	s_waitcnt lgkmcnt(0)
	s_barrier
	s_barrier
	ds_read_b128 v[100:103], v96
	ds_read_b128 v[104:107], v96 offset:1024
	ds_read_b128 v[108:111], v96 offset:2048
	ds_read_b128 v[112:115], v96 offset:3072
	ds_read_b128 v[116:119], v95
	ds_read_b128 v[120:123], v95 offset:1024
	ds_read_b128 v[124:127], v95 offset:2048
	ds_read_b128 v[128:131], v95 offset:3072
	v_readlane_b32 s8, v254, 24
	v_readlane_b32 s9, v254, 25
	s_mov_b32 m0, s66
	ds_read_b128 v[132:135], v94 offset:32768
	ds_read_b128 v[136:139], v94 offset:33792
	ds_read_b128 v[140:143], v94 offset:34816
	ds_read_b128 v[144:147], v94 offset:35840
	ds_read_b128 v[148:151], v94 offset:36864
	ds_read_b128 v[152:155], v94 offset:37888
	ds_read_b128 v[168:171], v94 offset:38912
	ds_read_b128 v[172:175], v94 offset:39936
	v_lshl_add_u64 v[156:157], s[8:9], 0, v[162:163]
	global_load_lds_dwordx4 v[156:157], off
	v_lshl_add_u64 v[156:157], s[8:9], 0, v[164:165]
	s_mov_b32 m0, s72
	s_nop 0
	global_load_lds_dwordx4 v[156:157], off
	s_waitcnt vmcnt(8)
	s_waitcnt lgkmcnt(0)
	s_barrier
	s_setprio 1
	s_waitcnt lgkmcnt(0)
	v_mfma_f32_16x16x128_f8f6f4 v[62:65], v[100:107], v[132:139], v[62:65]
	v_mfma_f32_16x16x128_f8f6f4 v[58:61], v[108:115], v[132:139], v[58:61]
	v_mfma_f32_16x16x128_f8f6f4 v[46:49], v[100:107], v[140:147], v[46:49]
	v_mfma_f32_16x16x128_f8f6f4 v[42:45], v[108:115], v[140:147], v[42:45]
	v_mfma_f32_16x16x128_f8f6f4 v[28:31], v[100:107], v[148:155], v[28:31]
	v_mfma_f32_16x16x128_f8f6f4 v[24:27], v[108:115], v[148:155], v[24:27]
	v_mfma_f32_16x16x128_f8f6f4 v[12:15], v[100:107], v[168:175], v[12:15]
	v_mfma_f32_16x16x128_f8f6f4 v[8:11], v[108:115], v[168:175], v[8:11]
	s_setprio 0
	s_setprio 1
	v_mfma_f32_16x16x128_f8f6f4 v[54:57], v[116:123], v[132:139], v[54:57]
	v_mfma_f32_16x16x128_f8f6f4 v[50:53], v[124:131], v[132:139], v[50:53]
	v_mfma_f32_16x16x128_f8f6f4 v[38:41], v[116:123], v[140:147], v[38:41]
	v_mfma_f32_16x16x128_f8f6f4 v[34:37], v[124:131], v[140:147], v[34:37]
	v_mfma_f32_16x16x128_f8f6f4 v[20:23], v[116:123], v[148:155], v[20:23]
	v_mfma_f32_16x16x128_f8f6f4 v[16:19], v[124:131], v[148:155], v[16:19]
	v_mfma_f32_16x16x128_f8f6f4 v[4:7], v[116:123], v[168:175], v[4:7]
	v_mfma_f32_16x16x128_f8f6f4 v[0:3], v[124:131], v[168:175], v[0:3]
	s_setprio 0
	s_barrier
	s_mov_b64 s[8:9], 0x280
	s_mov_b32 m0, s2
	v_lshl_add_u64 v[100:101], v[78:79], 0, s[8:9]
	global_load_lds_dwordx4 v[100:101], off
	v_lshl_add_u64 v[100:101], v[80:81], 0, s[8:9]
	s_mov_b32 m0, s73
	s_nop 0
	global_load_lds_dwordx4 v[100:101], off
	v_lshl_add_u64 v[100:101], s[16:17], 0, v[32:33]
	s_mov_b32 m0, s75
	s_nop 0
	global_load_lds_dwordx4 v[100:101], off
	v_lshl_add_u64 v[100:101], s[16:17], 0, v[166:167]
	s_mov_b32 m0, s76
	s_nop 0
	global_load_lds_dwordx4 v[100:101], off
	v_lshl_add_u64 v[100:101], v[90:91], 0, s[8:9]
	s_mov_b32 m0, s67
	s_nop 0
	global_load_lds_dwordx4 v[100:101], off
	v_lshl_add_u64 v[100:101], v[92:93], 0, s[8:9]
	s_mov_b32 m0, s74
	s_nop 0
	global_load_lds_dwordx4 v[100:101], off
	s_waitcnt vmcnt(8)
	s_waitcnt lgkmcnt(0)
	s_barrier
	s_barrier
	ds_read_b128 v[100:103], v98
	ds_read_b128 v[104:107], v98 offset:1024
	ds_read_b128 v[108:111], v98 offset:2048
	ds_read_b128 v[112:115], v98 offset:3072
	ds_read_b128 v[116:119], v97
	ds_read_b128 v[120:123], v97 offset:1024
	ds_read_b128 v[124:127], v97 offset:2048
	ds_read_b128 v[128:131], v97 offset:3072
	v_readlane_b32 s8, v254, 26
	v_readlane_b32 s9, v254, 27
	s_mov_b32 m0, s89
	ds_read_b128 v[132:135], v94
	ds_read_b128 v[136:139], v94 offset:1024
	ds_read_b128 v[140:143], v94 offset:2048
	ds_read_b128 v[144:147], v94 offset:3072
	ds_read_b128 v[148:151], v94 offset:4096
	ds_read_b128 v[152:155], v94 offset:5120
	ds_read_b128 v[168:171], v94 offset:6144
	ds_read_b128 v[172:175], v94 offset:7168
	v_lshl_add_u64 v[156:157], s[8:9], 0, v[162:163]
	global_load_lds_dwordx4 v[156:157], off
	v_lshl_add_u64 v[156:157], s[8:9], 0, v[164:165]
	s_mov_b32 m0, s88
	s_nop 0
	global_load_lds_dwordx4 v[156:157], off
	s_waitcnt vmcnt(8)
	s_waitcnt lgkmcnt(0)
	s_barrier
	s_setprio 1
	s_waitcnt lgkmcnt(0)
	v_mfma_f32_16x16x128_f8f6f4 v[62:65], v[100:107], v[132:139], v[62:65]
	v_mfma_f32_16x16x128_f8f6f4 v[58:61], v[108:115], v[132:139], v[58:61]
	v_mfma_f32_16x16x128_f8f6f4 v[46:49], v[100:107], v[140:147], v[46:49]
	v_mfma_f32_16x16x128_f8f6f4 v[42:45], v[108:115], v[140:147], v[42:45]
	v_mfma_f32_16x16x128_f8f6f4 v[28:31], v[100:107], v[148:155], v[28:31]
	v_mfma_f32_16x16x128_f8f6f4 v[24:27], v[108:115], v[148:155], v[24:27]
	v_mfma_f32_16x16x128_f8f6f4 v[12:15], v[100:107], v[168:175], v[12:15]
	v_mfma_f32_16x16x128_f8f6f4 v[8:11], v[108:115], v[168:175], v[8:11]
	s_setprio 0
	s_setprio 1
	v_mfma_f32_16x16x128_f8f6f4 v[54:57], v[116:123], v[132:139], v[54:57]
	v_mfma_f32_16x16x128_f8f6f4 v[50:53], v[124:131], v[132:139], v[50:53]
	v_mfma_f32_16x16x128_f8f6f4 v[38:41], v[116:123], v[140:147], v[38:41]
	v_mfma_f32_16x16x128_f8f6f4 v[34:37], v[124:131], v[140:147], v[34:37]
	v_mfma_f32_16x16x128_f8f6f4 v[20:23], v[116:123], v[148:155], v[20:23]
	v_mfma_f32_16x16x128_f8f6f4 v[16:19], v[124:131], v[148:155], v[16:19]
	v_mfma_f32_16x16x128_f8f6f4 v[4:7], v[116:123], v[168:175], v[4:7]
	v_mfma_f32_16x16x128_f8f6f4 v[0:3], v[124:131], v[168:175], v[0:3]
	s_setprio 0
	s_barrier
	s_mov_b64 s[8:9], 0x300
	s_mov_b32 m0, s85
	v_lshl_add_u64 v[100:101], v[78:79], 0, s[8:9]
	global_load_lds_dwordx4 v[100:101], off
	v_lshl_add_u64 v[100:101], v[80:81], 0, s[8:9]
	s_mov_b32 m0, s84
	s_nop 0
	global_load_lds_dwordx4 v[100:101], off
	v_lshl_add_u64 v[100:101], s[14:15], 0, v[32:33]
	s_mov_b32 m0, s87
	s_nop 0
	global_load_lds_dwordx4 v[100:101], off
	v_lshl_add_u64 v[100:101], s[14:15], 0, v[166:167]
	s_mov_b32 m0, s86
	s_nop 0
	global_load_lds_dwordx4 v[100:101], off
	v_lshl_add_u64 v[100:101], v[90:91], 0, s[8:9]
	s_mov_b32 m0, s77
	s_nop 0
	global_load_lds_dwordx4 v[100:101], off
	v_lshl_add_u64 v[100:101], v[92:93], 0, s[8:9]
	s_mov_b32 m0, s83
	s_nop 0
	global_load_lds_dwordx4 v[100:101], off
	s_waitcnt vmcnt(8)
	s_waitcnt lgkmcnt(0)
	s_barrier
	s_barrier
	ds_read_b128 v[100:103], v96
	ds_read_b128 v[104:107], v96 offset:1024
	ds_read_b128 v[108:111], v96 offset:2048
	ds_read_b128 v[112:115], v96 offset:3072
	ds_read_b128 v[116:119], v95
	ds_read_b128 v[120:123], v95 offset:1024
	ds_read_b128 v[124:127], v95 offset:2048
	ds_read_b128 v[128:131], v95 offset:3072
	v_readlane_b32 s8, v254, 28
	v_readlane_b32 s9, v254, 29
	s_mov_b32 m0, s66
	ds_read_b128 v[132:135], v94 offset:32768
	ds_read_b128 v[136:139], v94 offset:33792
	ds_read_b128 v[140:143], v94 offset:34816
	ds_read_b128 v[144:147], v94 offset:35840
	ds_read_b128 v[148:151], v94 offset:36864
	ds_read_b128 v[152:155], v94 offset:37888
	ds_read_b128 v[168:171], v94 offset:38912
	ds_read_b128 v[172:175], v94 offset:39936
	v_lshl_add_u64 v[156:157], s[8:9], 0, v[162:163]
	global_load_lds_dwordx4 v[156:157], off
	v_lshl_add_u64 v[156:157], s[8:9], 0, v[164:165]
	s_mov_b32 m0, s72
	s_nop 0
	global_load_lds_dwordx4 v[156:157], off
	s_waitcnt vmcnt(8)
	s_waitcnt lgkmcnt(0)
	s_barrier
	s_setprio 1
	s_waitcnt lgkmcnt(0)
	v_mfma_f32_16x16x128_f8f6f4 v[62:65], v[100:107], v[132:139], v[62:65]
	v_mfma_f32_16x16x128_f8f6f4 v[58:61], v[108:115], v[132:139], v[58:61]
	v_mfma_f32_16x16x128_f8f6f4 v[46:49], v[100:107], v[140:147], v[46:49]
	v_mfma_f32_16x16x128_f8f6f4 v[42:45], v[108:115], v[140:147], v[42:45]
	v_mfma_f32_16x16x128_f8f6f4 v[28:31], v[100:107], v[148:155], v[28:31]
	v_mfma_f32_16x16x128_f8f6f4 v[24:27], v[108:115], v[148:155], v[24:27]
	v_mfma_f32_16x16x128_f8f6f4 v[12:15], v[100:107], v[168:175], v[12:15]
	v_mfma_f32_16x16x128_f8f6f4 v[8:11], v[108:115], v[168:175], v[8:11]
	s_setprio 0
	s_setprio 1
	v_mfma_f32_16x16x128_f8f6f4 v[54:57], v[116:123], v[132:139], v[54:57]
	v_mfma_f32_16x16x128_f8f6f4 v[50:53], v[124:131], v[132:139], v[50:53]
	v_mfma_f32_16x16x128_f8f6f4 v[38:41], v[116:123], v[140:147], v[38:41]
	v_mfma_f32_16x16x128_f8f6f4 v[34:37], v[124:131], v[140:147], v[34:37]
	v_mfma_f32_16x16x128_f8f6f4 v[20:23], v[116:123], v[148:155], v[20:23]
	v_mfma_f32_16x16x128_f8f6f4 v[16:19], v[124:131], v[148:155], v[16:19]
	v_mfma_f32_16x16x128_f8f6f4 v[4:7], v[116:123], v[168:175], v[4:7]
	v_mfma_f32_16x16x128_f8f6f4 v[0:3], v[124:131], v[168:175], v[0:3]
	s_setprio 0
	s_barrier
	s_mov_b64 s[8:9], 0x380
	s_mov_b32 m0, s2
	v_lshl_add_u64 v[100:101], v[78:79], 0, s[8:9]
	global_load_lds_dwordx4 v[100:101], off
	v_lshl_add_u64 v[100:101], v[80:81], 0, s[8:9]
	s_mov_b32 m0, s73
	s_nop 0
	global_load_lds_dwordx4 v[100:101], off
	v_lshl_add_u64 v[100:101], s[10:11], 0, v[32:33]
	s_mov_b32 m0, s75
	s_nop 0
	global_load_lds_dwordx4 v[100:101], off
	v_lshl_add_u64 v[100:101], s[10:11], 0, v[166:167]
	s_mov_b32 m0, s76
	s_nop 0
	global_load_lds_dwordx4 v[100:101], off
	v_lshl_add_u64 v[100:101], v[90:91], 0, s[8:9]
	s_mov_b32 m0, s67
	s_nop 0
	global_load_lds_dwordx4 v[100:101], off
	v_lshl_add_u64 v[100:101], v[92:93], 0, s[8:9]
	s_mov_b32 m0, s74
	s_nop 0
	global_load_lds_dwordx4 v[100:101], off
	s_waitcnt vmcnt(8)
	s_waitcnt lgkmcnt(0)
	s_barrier
	s_barrier
	ds_read_b128 v[100:103], v98
	ds_read_b128 v[104:107], v98 offset:1024
	ds_read_b128 v[108:111], v98 offset:2048
	ds_read_b128 v[112:115], v98 offset:3072
	ds_read_b128 v[116:119], v97
	ds_read_b128 v[120:123], v97 offset:1024
	ds_read_b128 v[124:127], v97 offset:2048
	ds_read_b128 v[128:131], v97 offset:3072
	v_readlane_b32 s8, v254, 32
	v_readlane_b32 s9, v254, 33
	s_mov_b32 m0, s89
	ds_read_b128 v[132:135], v94
	ds_read_b128 v[136:139], v94 offset:1024
	ds_read_b128 v[140:143], v94 offset:2048
	ds_read_b128 v[144:147], v94 offset:3072
	ds_read_b128 v[148:151], v94 offset:4096
	ds_read_b128 v[152:155], v94 offset:5120
	ds_read_b128 v[166:169], v94 offset:6144
	ds_read_b128 v[170:173], v94 offset:7168
	v_lshl_add_u64 v[98:99], s[8:9], 0, v[162:163]
	global_load_lds_dwordx4 v[98:99], off
	v_lshl_add_u64 v[98:99], s[8:9], 0, v[164:165]
	s_mov_b32 m0, s88
	s_nop 0
	global_load_lds_dwordx4 v[98:99], off
	s_waitcnt vmcnt(8)
	s_waitcnt lgkmcnt(0)
	s_barrier
	s_setprio 1
	s_waitcnt lgkmcnt(0)
	v_mfma_f32_16x16x128_f8f6f4 v[62:65], v[100:107], v[132:139], v[62:65]
	v_mfma_f32_16x16x128_f8f6f4 v[58:61], v[108:115], v[132:139], v[58:61]
	v_mfma_f32_16x16x128_f8f6f4 v[46:49], v[100:107], v[140:147], v[46:49]
	v_mfma_f32_16x16x128_f8f6f4 v[42:45], v[108:115], v[140:147], v[42:45]
	v_mfma_f32_16x16x128_f8f6f4 v[28:31], v[100:107], v[148:155], v[28:31]
	v_mfma_f32_16x16x128_f8f6f4 v[24:27], v[108:115], v[148:155], v[24:27]
	v_mfma_f32_16x16x128_f8f6f4 v[12:15], v[100:107], v[166:173], v[12:15]
	v_mfma_f32_16x16x128_f8f6f4 v[8:11], v[108:115], v[166:173], v[8:11]
	s_setprio 0
	s_setprio 1
	v_mfma_f32_16x16x128_f8f6f4 v[54:57], v[116:123], v[132:139], v[54:57]
	v_mfma_f32_16x16x128_f8f6f4 v[50:53], v[124:131], v[132:139], v[50:53]
	v_mfma_f32_16x16x128_f8f6f4 v[38:41], v[116:123], v[140:147], v[38:41]
	v_mfma_f32_16x16x128_f8f6f4 v[34:37], v[124:131], v[140:147], v[34:37]
	v_mfma_f32_16x16x128_f8f6f4 v[20:23], v[116:123], v[148:155], v[20:23]
	v_mfma_f32_16x16x128_f8f6f4 v[16:19], v[124:131], v[148:155], v[16:19]
	v_mfma_f32_16x16x128_f8f6f4 v[4:7], v[116:123], v[166:173], v[4:7]
	v_mfma_f32_16x16x128_f8f6f4 v[0:3], v[124:131], v[166:173], v[0:3]
	s_setprio 0
	s_barrier
	s_mov_b32 m0, s85
	s_nop 0
	global_load_lds_dwordx4 v[78:79], off
	s_mov_b32 m0, s84
	s_nop 0
	global_load_lds_dwordx4 v[80:81], off
	s_mov_b32 m0, s87
	s_nop 0
	global_load_lds_dwordx4 v[82:83], off
	s_mov_b32 m0, s86
	s_nop 0
	global_load_lds_dwordx4 v[84:85], off
	s_mov_b32 m0, s77
	s_nop 0
	global_load_lds_dwordx4 v[90:91], off
	s_mov_b32 m0, s83
	s_nop 0
	global_load_lds_dwordx4 v[92:93], off
	s_waitcnt vmcnt(8)
	s_waitcnt lgkmcnt(0)
	s_barrier
	s_barrier
	ds_read_b128 v[78:81], v96
	ds_read_b128 v[82:85], v96 offset:1024
	ds_read_b128 v[98:101], v96 offset:2048
	ds_read_b128 v[102:105], v96 offset:3072
	ds_read_b128 v[106:109], v95
	ds_read_b128 v[110:113], v95 offset:1024
	ds_read_b128 v[114:117], v95 offset:2048
	ds_read_b128 v[118:121], v95 offset:3072
	s_mov_b32 m0, s66
	ds_read_b128 v[122:125], v94 offset:32768
	ds_read_b128 v[126:129], v94 offset:33792
	ds_read_b128 v[130:133], v94 offset:34816
	ds_read_b128 v[134:137], v94 offset:35840
	ds_read_b128 v[138:141], v94 offset:36864
	ds_read_b128 v[142:145], v94 offset:37888
	ds_read_b128 v[90:93], v94 offset:38912
	ds_read_b128 v[94:97], v94 offset:39936
	global_load_lds_dwordx4 v[86:87], off
	s_mov_b32 m0, s72
	s_nop 0
	global_load_lds_dwordx4 v[88:89], off
	s_waitcnt vmcnt(8)
	s_waitcnt lgkmcnt(0)
	s_barrier
	s_setprio 1
	s_waitcnt lgkmcnt(0)
	v_mfma_f32_16x16x128_f8f6f4 v[62:65], v[78:85], v[122:129], v[62:65]
	v_mfma_f32_16x16x128_f8f6f4 v[58:61], v[98:105], v[122:129], v[58:61]
	v_mfma_f32_16x16x128_f8f6f4 v[46:49], v[78:85], v[130:137], v[46:49]
	v_mfma_f32_16x16x128_f8f6f4 v[42:45], v[98:105], v[130:137], v[42:45]
	v_mfma_f32_16x16x128_f8f6f4 v[28:31], v[78:85], v[138:145], v[28:31]
	v_mfma_f32_16x16x128_f8f6f4 v[24:27], v[98:105], v[138:145], v[24:27]
	v_mfma_f32_16x16x128_f8f6f4 v[12:15], v[78:85], v[90:97], v[12:15]
	v_mfma_f32_16x16x128_f8f6f4 v[8:11], v[98:105], v[90:97], v[8:11]
	s_setprio 0
	s_setprio 1
	v_mfma_f32_16x16x128_f8f6f4 v[54:57], v[106:113], v[122:129], v[54:57]
	v_mfma_f32_16x16x128_f8f6f4 v[50:53], v[114:121], v[122:129], v[50:53]
	v_mfma_f32_16x16x128_f8f6f4 v[38:41], v[106:113], v[130:137], v[38:41]
	v_mfma_f32_16x16x128_f8f6f4 v[34:37], v[114:121], v[130:137], v[34:37]
	v_mfma_f32_16x16x128_f8f6f4 v[20:23], v[106:113], v[138:145], v[20:23]
	v_mfma_f32_16x16x128_f8f6f4 v[16:19], v[114:121], v[138:145], v[16:19]
	v_mfma_f32_16x16x128_f8f6f4 v[4:7], v[106:113], v[90:97], v[4:7]
	v_mfma_f32_16x16x128_f8f6f4 v[0:3], v[114:121], v[90:97], v[0:3]
	s_setprio 0
	s_barrier
	s_mov_b32 m0, s2
	s_nop 0
	global_load_lds_dwordx4 v[68:69], off
	s_mov_b32 m0, s73
	s_nop 0
	global_load_lds_dwordx4 v[70:71], off
	s_mov_b32 m0, s75
	s_nop 0
	global_load_lds_dwordx4 v[74:75], off
	s_mov_b32 m0, s76
	s_nop 0
	global_load_lds_dwordx4 v[76:77], off
	s_mov_b32 m0, s67
	s_nop 0
	global_load_lds_dwordx4 v[66:67], off
	s_mov_b32 m0, s74
	s_nop 0
	global_load_lds_dwordx4 v[72:73], off
	s_waitcnt vmcnt(8)
	s_waitcnt lgkmcnt(0)
	s_barrier
	s_barrier
	s_cbranch_scc1 .LBB0_487
	s_barrier

.LBB0_641:
	v_lshl_add_u64 v[0:1], s[66:67], 0, v[32:33]
	v_mov_b32_e32 v139, v33
	v_readlane_b32 s30, v253, 47
	v_lshl_add_u64 v[2:3], s[66:67], 0, v[138:139]
	v_mov_b32_e32 v143, v33
	v_readlane_b32 s31, v253, 48
	s_lshl_b32 s10, s10, 5
	s_add_i32 m0, s75, 0x18000
	v_lshl_add_u64 v[0:1], v[0:1], 0, s[38:39]
	v_lshl_add_u64 v[4:5], s[30:31], 0, v[142:143]
	v_mov_b32_e32 v141, v33
	s_lshl_b32 s16, s9, 13
	s_and_b32 s18, s10, 0x60
	s_nop 0
	global_load_lds_dwordx4 v[0:1], off
	v_lshl_add_u64 v[0:1], v[2:3], 0, s[38:39]
	s_add_i32 m0, s75, 0x1a000
	s_add_i32 s84, s75, 0x8000
	s_add_i32 s85, s75, 0xa000
	v_lshl_add_u64 v[6:7], s[30:31], 0, v[140:141]
	global_load_lds_dwordx4 v[0:1], off
	v_lshl_add_u64 v[0:1], v[4:5], 0, s[38:39]
	s_mov_b32 m0, s84
	s_add_u32 s10, s66, 0x40080
	global_load_lds_dwordx4 v[0:1], off
	v_lshl_add_u64 v[0:1], v[6:7], 0, s[38:39]
	s_mov_b32 m0, s85
	s_addc_u32 s11, s67, 0
	global_load_lds_dwordx4 v[0:1], off
	s_add_i32 m0, s75, 0x1c000
	v_lshl_add_u64 v[0:1], s[10:11], 0, v[32:33]
	global_load_lds_dwordx4 v[0:1], off
	v_lshl_add_u64 v[0:1], s[10:11], 0, v[138:139]
	s_add_i32 m0, s75, 0x1e000
	v_and_b32_e32 v2, 1, v181
	global_load_lds_dwordx4 v[0:1], off
	s_waitcnt vmcnt(8)
	s_barrier
	v_lshlrev_b32_e32 v1, 2, v213
	v_lshl_or_b32 v0, v213, 6, v214
	v_and_b32_e32 v1, 32, v1
	v_bitop3_b32 v0, v0, s16, v1 bitop3:0xde
	v_lshlrev_b32_e32 v1, 14, v181
	v_and_b32_e32 v1, 0xffff8000, v1
	v_lshl_add_u32 v1, v182, 11, v1
	v_lshl_or_b32 v1, v2, 6, v1
	v_lshl_add_u32 v144, v183, 1, v1
	v_lshlrev_b32_e32 v1, 14, v184
	v_lshl_or_b32 v158, s9, 6, v213
	s_cmpk_lt_u32 s8, 0x100
	v_and_b32_e32 v1, 0xffff8000, v1
	v_readlane_b32 s8, v253, 41
	s_waitcnt vmcnt(6)
	v_lshl_add_u32 v1, v185, 11, v1
	v_and_b32_e32 v2, 1, v184
	v_readlane_b32 s9, v253, 42
	v_lshl_or_b32 v1, v2, 6, v1
	s_mov_b32 s88, s8
	v_readlane_b32 s8, v253, 43
	v_lshl_or_b32 v159, s18, 7, v215
	s_cselect_b64 s[16:17], -1, 0
	v_or_b32_e32 v160, s18, v212
	v_mov_b32_e32 v145, v33
	v_lshl_add_u32 v146, v211, 1, v1
	v_mov_b32_e32 v147, v33
	s_mov_b32 s86, 0
	v_add_u32_e32 v161, 0, v0
	s_mov_b32 s87, s8
	s_mov_b64 s[10:11], s[30:31]
	s_barrier
	v_readlane_b32 s9, v253, 44
	s_branch .LBB0_644

.LBB0_1513:
	v_lshrrev_b32_e32 v18, 1, v12
	v_and_b32_e32 v18, 24, v18
	v_readlane_b32 s72, v253, 53
	v_and_b32_e32 v13, 15, v12
	v_lshlrev_b32_e32 v19, 1, v18
	v_lshlrev_b32_e32 v12, 2, v12
	s_lshl_b32 s9, s9, 5
	v_mov_b32_e32 v171, v33
	v_readlane_b32 s73, v253, 54
	v_lshl_or_b32 v204, s12, 6, v13
	v_lshl_or_b32 v13, v13, 6, v19
	s_lshl_b32 s12, s12, 13
	v_and_b32_e32 v12, 32, v12
	s_and_b32 s9, s9, 0x60
	s_add_i32 m0, s85, 0x18000
	v_lshl_add_u64 v[0:1], v[0:1], 0, s[38:39]
	v_lshl_add_u64 v[14:15], s[72:73], 0, v[170:171]
	v_mov_b32_e32 v169, v33
	v_bitop3_b32 v19, v13, s12, v12 bitop3:0xde
	s_lshl_b32 s12, s9, 7
	s_nop 0
	global_load_lds_dwordx4 v[0:1], off
	v_lshl_add_u64 v[0:1], v[2:3], 0, s[38:39]
	s_add_i32 m0, s85, 0x1a000
	s_add_i32 s89, s85, 0x8000
	s_add_i32 s90, s85, 0xa000
	v_lshl_add_u64 v[16:17], s[72:73], 0, v[168:169]
	v_bitop3_b32 v205, s12, v13, v12 bitop3:0xf6
	global_load_lds_dwordx4 v[0:1], off
	v_lshl_add_u64 v[0:1], v[14:15], 0, s[38:39]
	s_mov_b32 m0, s89
	s_add_u32 s12, s74, 0x20080
	global_load_lds_dwordx4 v[0:1], off
	v_lshl_add_u64 v[0:1], v[16:17], 0, s[38:39]
	s_mov_b32 m0, s90
	s_addc_u32 s13, s75, 0
	global_load_lds_dwordx4 v[0:1], off
	s_add_i32 m0, s85, 0x1c000
	v_lshl_add_u64 v[0:1], s[12:13], 0, v[32:33]
	global_load_lds_dwordx4 v[0:1], off
	v_lshl_add_u64 v[0:1], s[12:13], 0, v[166:167]
	s_add_i32 m0, s85, 0x1e000
	s_movk_i32 s13, 0x2a00
	global_load_lds_dwordx4 v[0:1], off
	s_waitcnt vmcnt(8)
	s_barrier
	v_lshrrev_b32_e32 v1, 1, v9
	v_mul_lo_u32 v0, v8, s13
	s_mov_b32 s12, 0x2a000
	s_cmpk_lt_u32 s8, 0x100
	v_or_b32_e32 v206, s9, v18
	v_mad_u64_u32 v[0:1], s[8:9], v1, s12, v[0:1]
	v_or_b32_e32 v0, v0, v10
	v_add_lshl_u32 v0, v0, v11, 1
	v_mov_b32_e32 v1, v33
	s_mov_b64 s[14:15], 0x2a0080
	v_lshl_add_u64 v[172:173], v[0:1], 0, s[14:15]
	v_lshrrev_b32_e32 v1, 1, v4
	v_mul_lo_u32 v0, v5, s13
	v_mad_u64_u32 v[0:1], s[8:9], v1, s12, v[0:1]
	s_waitcnt vmcnt(6)
	v_or_b32_e32 v0, v0, v6
	v_add_lshl_u32 v0, v0, v7, 1
	v_mov_b32_e32 v1, v33
	v_readlane_b32 s8, v253, 59
	s_cselect_b64 s[18:19], -1, 0
	v_lshl_add_u64 v[174:175], v[0:1], 0, s[14:15]
	s_mov_b32 s93, 0
	v_add_u32_e32 v207, 0, v19
	v_readlane_b32 s94, v253, 40
	s_mov_b32 s95, s8
	s_mov_b32 s91, 0
	s_barrier
	v_readlane_b32 s9, v253, 60
	s_branch .LBB0_1516

.LBB0_1630:
	v_readlane_b32 s48, v251, 4
	v_readlane_b32 s12, v255, 2
	v_readlane_b32 s49, v251, 5
	v_readlane_b32 s50, v251, 6
	v_readlane_b32 s51, v251, 7
	v_readlane_b32 s52, v251, 8
	v_readlane_b32 s53, v251, 9
	v_readlane_b32 s54, v251, 10
	v_readlane_b32 s55, v251, 11
	v_readlane_b32 s56, v251, 12
	v_readlane_b32 s57, v251, 13
	v_readlane_b32 s58, v251, 14
	v_readlane_b32 s59, v251, 15
	v_readlane_b32 s13, v255, 3
	v_readlane_b32 s44, v252, 36
	s_and_b64 s[12:13], s[12:13], exec
	v_readlane_b32 s62, v251, 18
	v_readlane_b32 s63, v251, 19
	v_readlane_b32 s45, v252, 37
	s_cselect_b32 s19, s45, s63
	s_cselect_b32 s18, s44, s62
	s_lshl_b32 s28, s2, 14
	s_lshl_b64 s[12:13], s[28:29], 2
	v_readlane_b32 s14, v251, 24
	v_readlane_b32 s15, v251, 25
	s_add_u32 s20, s14, s12
	s_addc_u32 s21, s15, s13
	v_readlane_b32 s12, v255, 4
	s_cmp_lg_u32 s12, 3
	v_bfe_u32 v16, v10, 4, 2
	v_readlane_b32 s72, v253, 63
	s_cselect_b64 s[30:31], -1, 0
	v_and_b32_e32 v11, 15, v10
	v_lshlrev_b32_e32 v17, 4, v16
	v_lshlrev_b32_e32 v10, 2, v10
	s_lshl_b32 s9, s9, 5
	v_mov_b32_e32 v201, v33
	v_readlane_b32 s73, v254, 0
	v_lshl_or_b32 v227, s10, 6, v11
	v_lshl_or_b32 v11, v11, 6, v17
	s_lshl_b32 s10, s10, 13
	v_and_b32_e32 v10, 32, v10
	s_and_b32 s9, s9, 0x60
	s_add_i32 m0, s86, 0x18000
	v_lshl_add_u64 v[0:1], v[0:1], 0, s[38:39]
	v_lshl_add_u64 v[12:13], s[72:73], 0, v[200:201]
	v_mov_b32_e32 v199, v33
	v_bitop3_b32 v17, v11, s10, v10 bitop3:0xde
	s_lshl_b32 s10, s9, 7
	s_nop 0
	global_load_lds_dwordx4 v[0:1], off
	v_lshl_add_u64 v[0:1], v[2:3], 0, s[38:39]
	s_add_i32 m0, s86, 0x1a000
	s_add_i32 s28, s86, 0x8000
	s_add_i32 s90, s86, 0xa000
	v_lshl_add_u64 v[14:15], s[72:73], 0, v[198:199]
	v_bitop3_b32 v228, s10, v11, v10 bitop3:0xf6
	global_load_lds_dwordx4 v[0:1], off
	v_lshl_add_u64 v[0:1], v[12:13], 0, s[38:39]
	s_mov_b32 m0, s28
	s_add_u32 s10, s74, 0x40080
	global_load_lds_dwordx4 v[0:1], off
	v_lshl_add_u64 v[0:1], v[14:15], 0, s[38:39]
	s_mov_b32 m0, s90
	s_addc_u32 s11, s75, 0
	global_load_lds_dwordx4 v[0:1], off
	s_add_i32 m0, s86, 0x1c000
	v_lshl_add_u64 v[0:1], s[10:11], 0, v[32:33]
	global_load_lds_dwordx4 v[0:1], off
	v_lshl_add_u64 v[0:1], s[10:11], 0, v[196:197]
	s_add_i32 m0, s86, 0x1e000
	v_readlane_b32 s46, v252, 38
	global_load_lds_dwordx4 v[0:1], off
	s_waitcnt vmcnt(8)
	s_barrier
	v_lshlrev_b32_e32 v0, 14, v8
	v_and_b32_e32 v0, 0xffff8000, v0
	v_lshl_add_u32 v0, v7, 11, v0
	v_and_b32_e32 v1, 1, v8
	v_lshl_or_b32 v0, v1, 6, v0
	v_lshl_add_u32 v202, v9, 1, v0
	v_lshlrev_b32_e32 v0, 14, v4
	v_readlane_b32 s47, v252, 39
	v_and_b32_e32 v0, 0xffff8000, v0
	s_waitcnt vmcnt(6)
	v_lshl_add_u32 v0, v5, 11, v0
	v_and_b32_e32 v1, 1, v4
	v_readlane_b32 s46, v251, 22
	s_cmpk_lt_u32 s8, 0x100
	v_lshl_or_b32 v229, v16, 3, s9
	v_lshl_or_b32 v0, v1, 6, v0
	v_readlane_b32 s8, v253, 59
	v_readlane_b32 s47, v251, 23
	s_cselect_b64 s[34:35], -1, 0
	s_mov_b32 s91, 0
	v_cmp_eq_u32_e64 s[10:11], 0, v16
	v_mov_b32_e32 v203, v33
	v_lshl_add_u32 v204, v6, 1, v0
	v_mov_b32_e32 v205, v33
	v_add_u32_e32 v230, 0, v17
	s_mov_b32 s92, s8
	v_readlane_b32 s93, v253, 40
	s_mov_b64 s[14:15], s[72:73]
	v_readlane_b32 s47, v254, 57
	v_readlane_b32 s60, v251, 16
	v_readlane_b32 s61, v251, 17
	v_readlane_b32 s48, v252, 40
	v_readlane_b32 s49, v252, 41
	v_readlane_b32 s50, v252, 42
	v_readlane_b32 s51, v252, 43
	v_readlane_b32 s52, v252, 44
	v_readlane_b32 s53, v252, 45
	v_readlane_b32 s54, v252, 46
	v_readlane_b32 s55, v252, 47
	v_readlane_b32 s56, v252, 48
	v_readlane_b32 s57, v252, 49
	v_readlane_b32 s58, v252, 50
	v_readlane_b32 s59, v252, 51
	v_readlane_b32 s13, v255, 5
	s_barrier
	v_readlane_b32 s9, v253, 60
	s_branch .LBB0_1633
